# per-XCD queues; MoBA units of one (b,h) run side by side (8 query blocks at a time, long ones first) to share K/V blocks in the XCD L2
# baseline (speedup 1.0000x reference)
; __global__ void __launch_bounds__(512) hybrid_fwd(Params p) {
;     ...
;             if (C.tid == 0) s_unit = (int)atomicAdd(ctl + 64 * (1 + l), 1u);
;             __syncthreads();
;             const int u = s_unit;
;             __syncthreads();
;             if (u >= 1024 + 1024 + 512) break;
;             const int v2 = u - 512, grpq = v2 >> 7, rq = v2 & 127;
;     ...
;             if (u >= 512 && rq < 64) lru_unit(C, p, l, grpq * 64 + rq);
;     ...
;             if (u >= 512 && rq >= 64) moba_unit(C, grpq * 64 + (rq - 64), (const float*)(C.ws + WS_KM) + (size_t)l * 128 * 512);
.Lq6_b:
	s_sub_u32 s19, s74, 64
	s_lshl_b32 s22, s22, 3
	s_lshr_b32 s20, s19, 4
	s_bitcmp1_b32 s19, 3
	s_cbranch_scc1 .Lq6_m
	s_lshl_b32 s20, s20, 7
	s_add_u32 s20, s20, s22
	s_and_b32 s19, s19, 7
	s_add_u32 s20, s20, s19
	s_add_u32 s74, s20, 512
	s_branch .Lq6_done
.Lq6_m:
	s_and_b32 s21, s20, 7
	s_add_u32 s22, s22, s21
	s_lshr_b32 s20, s20, 3
	s_lshl_b32 s20, s20, 3
	s_and_b32 s19, s19, 7
	s_add_u32 s20, s20, s19
	s_lshl_b32 s20, s20, 7
	s_add_u32 s20, s20, s22
	s_add_u32 s74, s20, 576
